# speedup vs baseline: 1.0223x; 1.0098x over previous
; __device__ __forceinline__ void qkt8(f32x16& p0, f32x16& p1, const char* Ks, const i32x8* q8, int r32, int hi) {
;     const int s127 = 127, s124 = 124;
;     const int sw0 = (r32 >> 1) & 7, sw1 = ((32 + r32) >> 1) & 7; const char* rp0 = Ks + r32 * 128; const char* rp1 = Ks + (32 + r32) * 128;
;     ...
;     {   i32x8 ka = K8LD(rp0, 0, sw0), kb = K8LD(rp1, 0, sw1);
;         asm volatile("s_waitcnt lgkmcnt(0)" ::: "memory");
;         asm volatile("v_mfma_scale_f32_32x32x64_f8f6f4 %0, %1, %2, -4.0, %3, %4 op_sel_hi:[0,0,0]" : "=&v"(p0) : "v"(ka), "v"(q8[0]), "v"(s127), "v"(s124));
;         asm volatile("v_mfma_scale_f32_32x32x64_f8f6f4 %0, %1, %2, -4.0, %3, %4 op_sel_hi:[0,0,0]" : "=&v"(p1) : "v"(kb), "v"(q8[0]), "v"(s127), "v"(s124)); }
;     {   i32x8 ka = K8LD(rp0, 1, sw0), kb = K8LD(rp1, 1, sw1);
;         asm volatile("s_waitcnt lgkmcnt(0)" ::: "memory");
;         asm volatile("v_mfma_scale_f32_32x32x64_f8f6f4 %0, %1, %2, %0, %3, %4 op_sel_hi:[0,0,0]" : "+v"(p0) : "v"(ka), "v"(q8[1]), "v"(s127), "v"(s124));
;         asm volatile("v_mfma_scale_f32_32x32x64_f8f6f4 %0, %1, %2, %0, %3, %4 op_sel_hi:[0,0,0]" : "+v"(p1) : "v"(kb), "v"(q8[1]), "v"(s127), "v"(s124)); }
; }
; __device__ __forceinline__ void finishSM8(f32x16& p0, f32x16& p1, float& l_reg, i32x8& pa) {
;     for (int r = 0; r < 16; ++r) p1[r] = __builtin_amdgcn_exp2f(p1[r]);
;     float ps = 0; for (int r = 0; r < 16; ++r) ps += p0[r]; for (int r = 0; r < 16; ++r) ps += p1[r];
;     l_reg += ps;
; #pragma unroll
;     for (int q = 0; q < 4; ++q) { int v = 0; v = __builtin_amdgcn_cvt_pk_bf8_f32(p0[4 * q], p0[4 * q + 1], v, false); v = __builtin_amdgcn_cvt_pk_bf8_f32(p0[4 * q + 2], p0[4 * q + 3], v, true); pa[q] = v; }
; #pragma unroll
;     for (int q = 0; q < 4; ++q) { int v = 0; v = __builtin_amdgcn_cvt_pk_bf8_f32(p1[4 * q], p1[4 * q + 1], v, false); v = __builtin_amdgcn_cvt_pk_bf8_f32(p1[4 * q + 2], p1[4 * q + 3], v, true); pa[4 + q] = v; }
; }
; template <bool EXPQ>
; __device__ __forceinline__ void pv8(f32x16* o, const char* Vs, const i32x8& pa, int r32, int hi, f32x16& pe) {
;     const int s127 = 127; const char* vp = Vs + r32 * 80 + hi * 32;
;     {   const i32x8 v0 = *(const i32x8*)(vp), v1 = *(const i32x8*)(vp + 32 * 80);
;         asm volatile("s_waitcnt lgkmcnt(0)" ::: "memory");
.LBB0_1027:
	s_lshl_b32 s50, s35, 14
	v_add_u32_e32 v252, s50, v201
	v_add_u32_e32 v250, v252, v202
	v_add_u32_e32 v251, v252, v203
	ds_read_b128 v[208:211], v250 offset:49152
	ds_read_b128 v[212:215], v251 offset:49152
	v_add_u32_e32 v250, v252, v205
	v_add_u32_e32 v251, v252, v206
	ds_read_b128 v[224:227], v250 offset:49152
	ds_read_b128 v[228:231], v251 offset:49152
	ds_read_b128 v[232:235], v250 offset:53248
	ds_read_b128 v[236:239], v251 offset:53248
.Lf4_loop:
	s_mov_b32 s47, s35
	s_mov_b32 s35, s44
	s_lshl_b32 s49, s47, 14
	s_lshl_b32 s50, s44, 14
	v_add_u32_e32 v250, v252, v202
	v_add_u32_e32 v251, v252, v203
	v_add_u32_e32 v253, s50, v207
	ds_read_b128 v[216:219], v250 offset:53248
	ds_read_b128 v[220:223], v251 offset:53248
	ds_read_b128 v[136:139], v253
	ds_read_b128 v[140:143], v253 offset:16
	ds_read_b128 v[240:243], v253 offset:2560
	ds_read_b128 v[244:247], v253 offset:2576
	v_cvt_pk_bf8_f32 v128, v64, v65
	v_cvt_pk_bf8_f32 v129, v68, v69
	v_cvt_pk_bf8_f32 v130, v72, v73
	v_cvt_pk_bf8_f32 v131, v76, v77
	v_exp_f32_e32 v80, v80
	v_exp_f32_e32 v81, v81
	s_waitcnt lgkmcnt(10)
	v_mfma_scale_f32_32x32x64_f8f6f4 v[96:111], v[208:215], v[152:159], -4.0, v189, v190 op_sel_hi:[0,0,0]
	v_cvt_pk_bf8_f32 v128, v66, v67 op_sel:[0,0,1]
	v_cvt_pk_bf8_f32 v129, v70, v71 op_sel:[0,0,1]
	ds_read_b128 v[208:211], v253 offset:5120
	ds_read_b128 v[212:215], v253 offset:5136
	v_cvt_pk_bf8_f32 v130, v74, v75 op_sel:[0,0,1]
	v_cvt_pk_bf8_f32 v131, v78, v79 op_sel:[0,0,1]
	v_exp_f32_e32 v84, v84
	v_exp_f32_e32 v85, v85
	v_exp_f32_e32 v88, v88
	s_waitcnt lgkmcnt(6)
	v_mfma_scale_f32_32x32x64_f8f6f4 v[112:127], v[216:223], v[152:159], -4.0, v189, v190 op_sel_hi:[0,0,0]
	v_exp_f32_e32 v89, v89
	v_exp_f32_e32 v92, v92
	v_exp_f32_e32 v93, v93
	ds_read_b128 v[216:219], v253 offset:7680
	ds_read_b128 v[220:223], v253 offset:7696
	v_exp_f32_e32 v82, v82
	v_exp_f32_e32 v83, v83
	v_exp_f32_e32 v86, v86
	v_exp_f32_e32 v87, v87
	v_exp_f32_e32 v90, v90
	v_mfma_scale_f32_32x32x64_f8f6f4 v[96:111], v[224:231], v[144:151], v[96:111], v189, v190 op_sel_hi:[0,0,0]
	v_exp_f32_e32 v91, v91
	v_exp_f32_e32 v94, v94
	v_exp_f32_e32 v95, v95
	v_cvt_pk_bf8_f32 v132, v80, v81
	v_cvt_pk_bf8_f32 v133, v84, v85
	v_cvt_pk_bf8_f32 v134, v88, v89
	v_cvt_pk_bf8_f32 v135, v92, v93
	v_mfma_scale_f32_32x32x64_f8f6f4 v[112:127], v[232:239], v[144:151], v[112:127], v189, v190 op_sel_hi:[0,0,0]
	v_cvt_pk_bf8_f32 v132, v82, v83 op_sel:[0,0,1]
	v_cvt_pk_bf8_f32 v133, v86, v87 op_sel:[0,0,1]
	v_cvt_pk_bf8_f32 v134, v90, v91 op_sel:[0,0,1]
	v_cvt_pk_bf8_f32 v135, v94, v95 op_sel:[0,0,1]
	v_lshl_add_u64 v[186:187], s[28:29], 0, v[182:183]
	v_add_co_u32_e32 v250, vcc, s62, v186
	v_lshl_add_u64 v[184:185], s[28:29], 0, v[180:181]
	v_add_f32_e32 v248, v64, v65
	v_addc_co_u32_e32 v251, vcc, 0, v187, vcc
	v_add_co_u32_e32 v252, vcc, s63, v184
	v_add_f32_e32 v249, v80, v81
	v_add_f32_e32 v248, v66, v248
	v_addc_co_u32_e32 v253, vcc, 0, v185, vcc
	global_load_dwordx4 v[172:175], v[250:251], off
	global_load_dwordx4 v[168:171], v[252:253], off
	v_add_f32_e32 v249, v82, v249
	s_waitcnt lgkmcnt(6)
	v_mfma_f32_32x32x64_f8f6f4 v[0:15], v[128:135], v[136:143], v[0:15] cbsz:1
	v_add_f32_e32 v248, v67, v248
	v_add_f32_e32 v249, v83, v249
	v_add_f32_e32 v248, v68, v248
	v_add_f32_e32 v249, v84, v249
	v_add_f32_e32 v248, v69, v248
	v_add_f32_e32 v249, v85, v249
	v_add_f32_e32 v248, v70, v248
	v_add_f32_e32 v249, v86, v249
	v_add_f32_e32 v248, v71, v248
	v_add_f32_e32 v249, v87, v249
	v_add_f32_e32 v248, v72, v248
	v_add_f32_e32 v249, v88, v249
	v_add_f32_e32 v248, v73, v248
	v_add_f32_e32 v249, v89, v249
	s_waitcnt lgkmcnt(4)
	v_mfma_f32_32x32x64_f8f6f4 v[16:31], v[128:135], v[240:247], v[16:31] cbsz:1
	s_lshl_b32 s44, s46, 14
	v_add_u32_e32 v250, s44, v199
	s_add_i32 s48, s44, 0
	v_add_u32_e32 v251, s48, v198
	v_add_u32_e32 v252, s48, v200
	s_waitcnt vmcnt(2)
	ds_write_b128 v250, v[164:167]
	ds_write_b64 v251, v[160:161] offset:49152
	ds_write_b64 v252, v[162:163] offset:49152
	v_add_f32_e32 v248, v74, v248
	v_add_f32_e32 v249, v90, v249
	v_add_f32_e32 v248, v75, v248
	v_add_f32_e32 v249, v91, v249
	v_add_f32_e32 v248, v76, v248
	v_add_f32_e32 v249, v92, v249
	v_exp_f32_e32 v96, v96
	v_exp_f32_e32 v97, v97
	v_exp_f32_e32 v98, v98
	v_exp_f32_e32 v99, v99
	s_waitcnt lgkmcnt(5)
	v_mfma_f32_32x32x64_f8f6f4 v[32:47], v[128:135], v[208:215], v[32:47] cbsz:1
	v_add_f32_e32 v248, v77, v248
	v_add_f32_e32 v249, v93, v249
	v_add_f32_e32 v248, v78, v248
	v_add_f32_e32 v249, v94, v249
	v_exp_f32_e32 v100, v100
	v_exp_f32_e32 v101, v101
	v_exp_f32_e32 v102, v102
	v_exp_f32_e32 v103, v103
	v_exp_f32_e32 v104, v104
	v_exp_f32_e32 v105, v105
	s_waitcnt lgkmcnt(0)
	s_barrier
; __device__ __forceinline__ void qkt8(f32x16& p0, f32x16& p1, const char* Ks, const i32x8* q8, int r32, int hi) {
;     const int s127 = 127, s124 = 124;
;     const int sw0 = (r32 >> 1) & 7, sw1 = ((32 + r32) >> 1) & 7; const char* rp0 = Ks + r32 * 128; const char* rp1 = Ks + (32 + r32) * 128;
;     ...
;     {   i32x8 ka = K8LD(rp0, 0, sw0), kb = K8LD(rp1, 0, sw1);
;         asm volatile("s_waitcnt lgkmcnt(0)" ::: "memory");
;         asm volatile("v_mfma_scale_f32_32x32x64_f8f6f4 %0, %1, %2, -4.0, %3, %4 op_sel_hi:[0,0,0]" : "=&v"(p0) : "v"(ka), "v"(q8[0]), "v"(s127), "v"(s124));
;         asm volatile("v_mfma_scale_f32_32x32x64_f8f6f4 %0, %1, %2, -4.0, %3, %4 op_sel_hi:[0,0,0]" : "=&v"(p1) : "v"(kb), "v"(q8[0]), "v"(s127), "v"(s124)); }
;     {   i32x8 ka = K8LD(rp0, 1, sw0), kb = K8LD(rp1, 1, sw1);
;         asm volatile("s_waitcnt lgkmcnt(0)" ::: "memory");
;         asm volatile("v_mfma_scale_f32_32x32x64_f8f6f4 %0, %1, %2, %0, %3, %4 op_sel_hi:[0,0,0]" : "+v"(p0) : "v"(ka), "v"(q8[1]), "v"(s127), "v"(s124));
;         asm volatile("v_mfma_scale_f32_32x32x64_f8f6f4 %0, %1, %2, %0, %3, %4 op_sel_hi:[0,0,0]" : "+v"(p1) : "v"(kb), "v"(q8[1]), "v"(s127), "v"(s124)); }
; }
; __device__ __forceinline__ void finishSM8(f32x16& p0, f32x16& p1, float& l_reg, i32x8& pa) {
;     for (int r = 0; r < 16; ++r) p1[r] = __builtin_amdgcn_exp2f(p1[r]);
;     float ps = 0; for (int r = 0; r < 16; ++r) ps += p0[r]; for (int r = 0; r < 16; ++r) ps += p1[r];
;     l_reg += ps;
; #pragma unroll
;     for (int q = 0; q < 4; ++q) { int v = 0; v = __builtin_amdgcn_cvt_pk_bf8_f32(p0[4 * q], p0[4 * q + 1], v, false); v = __builtin_amdgcn_cvt_pk_bf8_f32(p0[4 * q + 2], p0[4 * q + 3], v, true); pa[q] = v; }
; #pragma unroll
;     for (int q = 0; q < 4; ++q) { int v = 0; v = __builtin_amdgcn_cvt_pk_bf8_f32(p1[4 * q], p1[4 * q + 1], v, false); v = __builtin_amdgcn_cvt_pk_bf8_f32(p1[4 * q + 2], p1[4 * q + 3], v, true); pa[4 + q] = v; }
; }
; template <bool EXPQ>
; __device__ __forceinline__ void pv8(f32x16* o, const char* Vs, const i32x8& pa, int r32, int hi, f32x16& pe) {
;     const int s127 = 127; const char* vp = Vs + r32 * 80 + hi * 32;
;     {   const i32x8 v0 = *(const i32x8*)(vp), v1 = *(const i32x8*)(vp + 32 * 80);
;         asm volatile("s_waitcnt lgkmcnt(0)" ::: "memory");
	v_add_u32_e32 v252, s48, v201
	v_add_u32_e32 v250, v252, v202
	v_add_u32_e32 v251, v252, v203
	ds_read_b128 v[208:211], v250 offset:49152
	ds_read_b128 v[212:215], v251 offset:49152
	v_add_u32_e32 v250, v252, v205
	v_add_u32_e32 v251, v252, v206
	ds_read_b128 v[224:227], v250 offset:49152
	ds_read_b128 v[228:231], v251 offset:49152
	ds_read_b128 v[232:235], v250 offset:53248
	ds_read_b128 v[236:239], v251 offset:53248
	v_mfma_f32_32x32x64_f8f6f4 v[48:63], v[128:135], v[216:223], v[48:63] cbsz:1
	v_add_f32_e32 v248, v79, v248
	v_add_f32_e32 v249, v95, v249
	v_add_f32_e32 v178, v178, v248
	v_add_f32_e32 v178, v178, v249
	v_exp_f32_e32 v106, v106
	v_exp_f32_e32 v107, v107
	v_exp_f32_e32 v108, v108
	v_exp_f32_e32 v109, v109
	v_exp_f32_e32 v110, v110
	v_exp_f32_e32 v111, v111
	v_add_u32_e32 v250, v252, v202
	v_add_u32_e32 v251, v252, v203
	v_add_u32_e32 v253, s49, v207
	s_add_i32 s49, s50, 0
	ds_read_b128 v[216:219], v250 offset:53248
	ds_read_b128 v[220:223], v251 offset:53248
	ds_read_b128 v[136:139], v253
	ds_read_b128 v[140:143], v253 offset:16
	ds_read_b128 v[240:243], v253 offset:2560
	ds_read_b128 v[244:247], v253 offset:2576
	v_cvt_pk_bf8_f32 v128, v96, v97
	v_cvt_pk_bf8_f32 v129, v100, v101
	v_cvt_pk_bf8_f32 v130, v104, v105
	v_cvt_pk_bf8_f32 v131, v108, v109
	v_exp_f32_e32 v112, v112
	v_exp_f32_e32 v113, v113
	s_waitcnt lgkmcnt(10)
	v_mfma_scale_f32_32x32x64_f8f6f4 v[64:79], v[208:215], v[152:159], -4.0, v189, v190 op_sel_hi:[0,0,0]
	v_cvt_pk_bf8_f32 v128, v98, v99 op_sel:[0,0,1]
	v_cvt_pk_bf8_f32 v129, v102, v103 op_sel:[0,0,1]
	ds_read_b128 v[208:211], v253 offset:5120
	ds_read_b128 v[212:215], v253 offset:5136
	v_cvt_pk_bf8_f32 v130, v106, v107 op_sel:[0,0,1]
	v_cvt_pk_bf8_f32 v131, v110, v111 op_sel:[0,0,1]
	v_exp_f32_e32 v116, v116
	v_exp_f32_e32 v117, v117
	v_exp_f32_e32 v120, v120
	s_waitcnt lgkmcnt(6)
	v_mfma_scale_f32_32x32x64_f8f6f4 v[80:95], v[216:223], v[152:159], -4.0, v189, v190 op_sel_hi:[0,0,0]
	v_exp_f32_e32 v121, v121
	v_exp_f32_e32 v124, v124
	v_exp_f32_e32 v125, v125
	ds_read_b128 v[216:219], v253 offset:7680
	ds_read_b128 v[220:223], v253 offset:7696
	v_exp_f32_e32 v114, v114
	v_exp_f32_e32 v115, v115
	v_exp_f32_e32 v118, v118
	v_exp_f32_e32 v119, v119
	v_exp_f32_e32 v122, v122
	v_mfma_scale_f32_32x32x64_f8f6f4 v[64:79], v[224:231], v[144:151], v[64:79], v189, v190 op_sel_hi:[0,0,0]
	v_exp_f32_e32 v123, v123
	v_exp_f32_e32 v126, v126
	v_exp_f32_e32 v127, v127
	v_cvt_pk_bf8_f32 v132, v112, v113
	v_cvt_pk_bf8_f32 v133, v116, v117
	v_cvt_pk_bf8_f32 v134, v120, v121
	v_cvt_pk_bf8_f32 v135, v124, v125
	v_mfma_scale_f32_32x32x64_f8f6f4 v[80:95], v[232:239], v[144:151], v[80:95], v189, v190 op_sel_hi:[0,0,0]
	v_cvt_pk_bf8_f32 v132, v114, v115 op_sel:[0,0,1]
	v_cvt_pk_bf8_f32 v133, v118, v119 op_sel:[0,0,1]
	v_cvt_pk_bf8_f32 v134, v122, v123 op_sel:[0,0,1]
	v_cvt_pk_bf8_f32 v135, v126, v127 op_sel:[0,0,1]
	s_cmp_ge_u32 s3, s69
	s_cselect_b64 s[44:45], -1, 0
	s_and_b64 vcc, exec, s[44:45]
	s_cbranch_vccnz .Lf4_skip
	v_add_co_u32_e32 v160, vcc, 0x49730000, v186
	v_add_f32_e32 v248, v96, v97
	v_add_f32_e32 v249, v112, v113
	v_addc_co_u32_e32 v161, vcc, 0, v187, vcc
	v_add_co_u32_e32 v162, vcc, 0x48b30000, v184
	v_add_f32_e32 v248, v98, v248
	v_add_f32_e32 v249, v114, v249
	v_addc_co_u32_e32 v163, vcc, 0, v185, vcc
	global_load_dwordx4 v[164:167], v[160:161], off
	s_nop 0
	global_load_dwordx4 v[160:163], v[162:163], off
	s_branch .Lf4_sedone

; #define SBAR() __builtin_amdgcn_sched_barrier(0)
; #define SWAIT() do { if constexpr (FIXED) asm volatile("s_waitcnt vmcnt(2)" ::: "memory"); else if constexpr (SD == 2) asm volatile("s_waitcnt vmcnt(4)" ::: "memory"); else asm volatile("s_waitcnt vmcnt(0)" ::: "memory"); } while (0)
; #define PVX(VOFF, PE) do { if constexpr (FIXED) pv8<true>(o, (const char*)V_lds + (VOFF), pa8, r32, hi, PE); else pv_d0(o, vb0 + (VOFF), pa0, pa1, pa2, pa3); } while (0)
; #define PSMG(P0, P1, MN, AL) do { if constexpr (!FIXED) partialSM(P0, P1, m_reg, MN, AL); } while (0)
; #define RESCX(a) do { if constexpr (!FIXED) RESC(a); } while (0)
; template <bool EXPQ>
; __device__ __forceinline__ void pv8(f32x16* o, const char* Vs, const i32x8& pa, int r32, int hi, f32x16& pe) {
;     const int s127 = 127; const char* vp = Vs + r32 * 80 + hi * 32;
;     {   const i32x8 v0 = *(const i32x8*)(vp), v1 = *(const i32x8*)(vp + 32 * 80);
;         asm volatile("s_waitcnt lgkmcnt(0)" ::: "memory");
;         asm volatile("v_mfma_scale_f32_32x32x64_f8f6f4 %0, %1, %2, %0, %3, %3 op_sel_hi:[0,0,0] cbsz:1" : "+v"(o[0]) : "v"(pa), "v"(v0), "v"(s127));
;         asm volatile("v_mfma_scale_f32_32x32x64_f8f6f4 %0, %1, %2, %0, %3, %3 op_sel_hi:[0,0,0] cbsz:1" : "+v"(o[1]) : "v"(pa), "v"(v1), "v"(s127)); }
;     {   const i32x8 v2 = *(const i32x8*)(vp + 64 * 80), v3 = *(const i32x8*)(vp + 96 * 80);
;         if constexpr (EXPQ) { for (int r = 0; r < 16; ++r) pe[r] = __builtin_amdgcn_exp2f(pe[r]); asm volatile("" : "+v"(pe)); }
;         asm volatile("s_waitcnt lgkmcnt(0)" ::: "memory");
;         asm volatile("v_mfma_scale_f32_32x32x64_f8f6f4 %0, %1, %2, %0, %3, %3 op_sel_hi:[0,0,0] cbsz:1" : "+v"(o[2]) : "v"(pa), "v"(v2), "v"(s127));
;         asm volatile("v_mfma_scale_f32_32x32x64_f8f6f4 %0, %1, %2, %0, %3, %3 op_sel_hi:[0,0,0] cbsz:1" : "+v"(o[3]) : "v"(pa), "v"(v3), "v"(s127)); }
; }
; template <bool FIXED> ...
;     ...
;         if (SD == 1 || j + 3 < NT) SLOAD(SE, (j + 1 + SD) * KVBLK); SBAR();
;         PVX(bp * (int)SHM_V, pA0); PSMG(pA0, pA1, mnA, alA);
;         SWAIT(); SWRITE(bn, SO);
;         RESCX(alA); __syncthreads();
;         { const int t_ = bp; bp = bc; bc = bn; bn = t_; }
;     }
.Lf4_wr:
	ds_write_b128 v250, v[172:175]
	ds_write_b64 v251, v[168:169] offset:49152
	ds_write_b64 v252, v[170:171] offset:49152
	v_add_f32_e32 v248, v106, v248
	v_add_f32_e32 v249, v122, v249
	v_add_f32_e32 v248, v107, v248
	v_add_f32_e32 v249, v123, v249
	v_add_f32_e32 v248, v108, v248
	v_add_f32_e32 v249, v124, v249
	v_exp_f32_e32 v64, v64
	v_exp_f32_e32 v65, v65
	v_exp_f32_e32 v66, v66
	v_exp_f32_e32 v67, v67
	s_waitcnt lgkmcnt(5)
	v_mfma_f32_32x32x64_f8f6f4 v[32:47], v[128:135], v[208:215], v[32:47] cbsz:1
	v_add_f32_e32 v248, v109, v248
	v_add_f32_e32 v249, v125, v249
	v_add_f32_e32 v248, v110, v248
	v_add_f32_e32 v249, v126, v249
	v_exp_f32_e32 v68, v68
	v_exp_f32_e32 v69, v69
	v_exp_f32_e32 v70, v70
	v_exp_f32_e32 v71, v71
	v_exp_f32_e32 v72, v72
	v_exp_f32_e32 v73, v73
	s_waitcnt lgkmcnt(0)
	s_barrier
	s_lshl_b32 s50, s35, 14
	v_add_u32_e32 v252, s50, v201
	v_add_u32_e32 v250, v252, v202
	v_add_u32_e32 v251, v252, v203
	ds_read_b128 v[208:211], v250 offset:49152
	ds_read_b128 v[212:215], v251 offset:49152
	v_add_u32_e32 v250, v252, v205
	v_add_u32_e32 v251, v252, v206
	ds_read_b128 v[224:227], v250 offset:49152
	ds_read_b128 v[228:231], v251 offset:49152
	ds_read_b128 v[232:235], v250 offset:53248
	ds_read_b128 v[236:239], v251 offset:53248
	v_mfma_f32_32x32x64_f8f6f4 v[48:63], v[128:135], v[216:223], v[48:63] cbsz:1
	v_add_f32_e32 v248, v111, v248
	v_add_f32_e32 v249, v127, v249
	v_add_f32_e32 v178, v178, v248
	v_add_f32_e32 v178, v178, v249
	v_exp_f32_e32 v74, v74
	v_exp_f32_e32 v75, v75
	v_exp_f32_e32 v76, v76
	v_exp_f32_e32 v77, v77
	v_exp_f32_e32 v78, v78
	v_exp_f32_e32 v79, v79
	v_lshl_add_u64 v[180:181], v[180:181], 0, s[22:23]
	v_lshl_add_u64 v[182:183], v[182:183], 0, s[22:23]
	s_add_i32 s3, s3, 2
	s_and_b64 vcc, exec, s[44:45]
	s_cbranch_vccnz .LBB0_1031
	s_mov_b32 s44, s46
	s_mov_b32 s46, s47
	s_branch .Lf4_loop
